# v32 with every per-cluster s_setprio flip deleted from the K-loops and one static s_setprio 1 for waves 0-3 per tile (strategy lever 4)
# speedup vs baseline: 1.0025x; 1.0025x over previous
;     __host__ __device__ bool next(int i, Unit& u) const { const bool ok = StaticOrder::next(i, u); u.lm = 0; u.ln = 0; return ok; }
; template <class Epi, class Sched, bool ALIGN_EPI = false, bool SP2 = false>
; __device__ __forceinline__ void gemm_phase(PG8_LAS unsigned char* lds, const Gemm g, const Sched& S, const Epi& E, const int wave_id) {
;     ...
;         const bool has_next = S.next(ui + 1, nxt);
;         const char* nA = has_next ? (const char*)g.A + (size_t)nxt.lm * tstep : cA; const char* nB = has_next ? (const char*)g.Bt + (size_t)nxt.ln * tstep : cB;
; #pragma unroll 1
;         for (int t = 0; t < nt; t += 2) {
;             const bool last = (t == nt - 2);
;             const char* a1 = cA + (size_t)(t + 1) * kstep;
;             const char* a2 = last ? nA : cA + (size_t)(t + 2) * kstep; const char* b2 = last ? nB : cB + (size_t)(t + 2) * kstep;
;             const char* a3 = a2 + kstep; const char* b3 = b2 + kstep;
.LBB0_173:
	s_ashr_i32 s15, s14, 31
	s_lshl_b64 s[16:17], s[14:15], 20
	s_add_u32 s16, s49, s16
	s_addc_u32 s17, s52, s17
	s_and_b64 s[18:19], s[38:39], exec
	s_cselect_b32 s15, s17, s21
	s_cselect_b32 s41, s16, s20
	s_ashr_i32 s13, s12, 31
	s_lshl_b64 s[18:19], s[12:13], 20
	s_add_u32 s18, s47, s18
	s_addc_u32 s19, s48, s19
	s_and_b64 s[44:45], s[38:39], exec
	s_cselect_b32 s13, s19, s43
	s_cselect_b32 s72, s18, s42
	s_add_u32 s20, s20, 0x80080
	s_addc_u32 s21, s21, 0
	s_add_u32 s73, s42, 0x100
	s_addc_u32 s74, s43, 0
	s_mov_b32 s75, -2
	v_add_u32_e32 v230, 0x10000, v171
	s_cmp_eq_u64 s[10:11], 0
	s_cbranch_scc1 .Lprio_g1
	s_setprio 1

;     __host__ __device__ bool next(int i, Unit& u) const { const bool ok = StaticOrder::next(i, u); u.lm = 0; u.ln = 0; return ok; }
; template <class Epi, class Sched, bool ALIGN_EPI = false, bool SP2 = false>
; __device__ __forceinline__ void gemm_phase(PG8_LAS unsigned char* lds, const Gemm g, const Sched& S, const Epi& E, const int wave_id) {
;     ...
;         const bool has_next = S.next(ui + 1, nxt);
;         const char* nA = has_next ? (const char*)g.A + (size_t)nxt.lm * tstep : cA; const char* nB = has_next ? (const char*)g.Bt + (size_t)nxt.ln * tstep : cB;
; #pragma unroll 1
;         for (int t = 0; t < nt; t += 2) {
;             const bool last = (t == nt - 2);
;             const char* a1 = cA + (size_t)(t + 1) * kstep;
;             const char* a2 = last ? nA : cA + (size_t)(t + 2) * kstep; const char* b2 = last ? nB : cB + (size_t)(t + 2) * kstep;
;             const char* a3 = a2 + kstep; const char* b3 = b2 + kstep;
.LBB0_523:
	s_ashr_i32 s15, s14, 31
	s_lshl_b64 s[16:17], s[14:15], 20
	s_add_u32 s16, s47, s16
	s_addc_u32 s17, s48, s17
	s_and_b64 s[18:19], s[38:39], exec
	s_cselect_b32 s15, s17, s41
	s_cselect_b32 s21, s16, s40
	s_ashr_i32 s13, s12, 31
	s_lshl_b64 s[18:19], s[12:13], 20
	s_add_u32 s18, s49, s18
	s_addc_u32 s19, s52, s19
	s_and_b64 s[44:45], s[38:39], exec
	s_cselect_b32 s13, s19, s43
	s_cselect_b32 s73, s18, s42
	s_add_u32 s40, s40, 0x80080
	s_addc_u32 s41, s41, 0
	s_add_u32 s74, s42, 0x100
	s_addc_u32 s75, s43, 0
	s_mov_b32 s76, -2
	v_add_u32_e32 v226, 0x10000, v218
	s_cmp_eq_u64 s[10:11], 0
	s_cbranch_scc1 .Lprio_g2
	s_setprio 1

;     __host__ __device__ bool next(int i, Unit& u) const { const bool ok = StaticOrder::next(i, u); u.lm = 0; u.ln = 0; return ok; }
; template <class Epi, class Sched, bool ALIGN_EPI = false, bool SP2 = false>
; __device__ __forceinline__ void gemm_phase(PG8_LAS unsigned char* lds, const Gemm g, const Sched& S, const Epi& E, const int wave_id) {
;     ...
;         const bool has_next = S.next(ui + 1, nxt);
;         const char* nA = has_next ? (const char*)g.A + (size_t)nxt.lm * tstep : cA; const char* nB = has_next ? (const char*)g.Bt + (size_t)nxt.ln * tstep : cB;
; #pragma unroll 1
;         for (int t = 0; t < nt; t += 2) {
;             const bool last = (t == nt - 2);
;             const char* a1 = cA + (size_t)(t + 1) * kstep;
;             const char* a2 = last ? nA : cA + (size_t)(t + 2) * kstep; const char* b2 = last ? nB : cB + (size_t)(t + 2) * kstep;
;             const char* a3 = a2 + kstep; const char* b3 = b2 + kstep;
.LBB0_640:
	s_ashr_i32 s15, s14, 31
	s_lshl_b64 s[16:17], s[14:15], 20
	s_add_u32 s16, s47, s16
	s_addc_u32 s17, s48, s17
	s_and_b64 s[18:19], s[38:39], exec
	s_cselect_b32 s15, s17, s21
	s_cselect_b32 s71, s16, s20
	s_ashr_i32 s13, s12, 31
	s_lshl_b64 s[18:19], s[12:13], 20
	s_add_u32 s18, s49, s18
	s_addc_u32 s19, s52, s19
	s_and_b64 s[44:45], s[38:39], exec
	s_cselect_b32 s13, s19, s43
	s_cselect_b32 s72, s18, s42
	s_add_u32 s20, s20, 0x80080
	s_addc_u32 s21, s21, 0
	s_add_u32 s73, s42, 0x100
	s_addc_u32 s74, s43, 0
	s_mov_b32 s75, -2
	v_add_u32_e32 v144, 0x10000, v147
	s_cmp_eq_u64 s[10:11], 0
	s_cbranch_scc1 .Lprio_g3
	s_setprio 1

;     __host__ __device__ bool next(int i, Unit& u) const { const bool ok = StaticOrder::next(i, u); u.lm = 0; u.ln = 0; return ok; }
; template <class Epi, class Sched, bool ALIGN_EPI = false, bool SP2 = false>
; __device__ __forceinline__ void gemm_phase(PG8_LAS unsigned char* lds, const Gemm g, const Sched& S, const Epi& E, const int wave_id) {
;     ...
;         const bool has_next = S.next(ui + 1, nxt);
;         const char* nA = has_next ? (const char*)g.A + (size_t)nxt.lm * tstep : cA; const char* nB = has_next ? (const char*)g.Bt + (size_t)nxt.ln * tstep : cB;
; #pragma unroll 1
;         for (int t = 0; t < nt; t += 2) {
;             const bool last = (t == nt - 2);
;             const char* a1 = cA + (size_t)(t + 1) * kstep;
;             const char* a2 = last ? nA : cA + (size_t)(t + 2) * kstep; const char* b2 = last ? nB : cB + (size_t)(t + 2) * kstep;
;             const char* a3 = a2 + kstep; const char* b3 = b2 + kstep;
.LBB0_758:
	s_add_u32 s74, s20, 0x100
	s_addc_u32 s75, s21, 0
	s_mov_b32 s76, -2
	v_add_u32_e32 v226, 0x10000, v218
	s_cmp_eq_u64 s[10:11], 0
	s_cbranch_scc1 .Lprio_g4
	s_setprio 1

;     __host__ __device__ bool next(int i, Unit& u) const { const bool ok = StaticOrder::next(i, u); u.lm = 0; u.ln = 0; return ok; }
; template <class Epi, class Sched, bool ALIGN_EPI = false, bool SP2 = false>
; __device__ __forceinline__ void gemm_phase(PG8_LAS unsigned char* lds, const Gemm g, const Sched& S, const Epi& E, const int wave_id) {
;     ...
;         const bool has_next = S.next(ui + 1, nxt);
;         const char* nA = has_next ? (const char*)g.A + (size_t)nxt.lm * tstep : cA; const char* nB = has_next ? (const char*)g.Bt + (size_t)nxt.ln * tstep : cB;
; #pragma unroll 1
;         for (int t = 0; t < nt; t += 2) {
;             const bool last = (t == nt - 2);
;             const char* a1 = cA + (size_t)(t + 1) * kstep;
;             const char* a2 = last ? nA : cA + (size_t)(t + 2) * kstep; const char* b2 = last ? nB : cB + (size_t)(t + 2) * kstep;
;             const char* a3 = a2 + kstep; const char* b3 = b2 + kstep;
.LBB0_903:
	s_ashr_i32 s21, s20, 31
	s_lshl_b64 s[42:43], s[20:21], 20
	s_add_u32 s42, s8, s42
	s_addc_u32 s43, s9, s43
	s_and_b64 s[44:45], s[40:41], exec
	s_cselect_b32 s21, s43, s47
	s_cselect_b32 s49, s42, s46
	s_ashr_i32 s19, s18, 31
	s_lshl_b64 s[44:45], s[18:19], 20
	s_add_u32 s44, s65, s44
	s_addc_u32 s45, s68, s45
	s_and_b64 s[80:81], s[40:41], exec
	s_cselect_b32 s19, s45, s53
	s_cselect_b32 s79, s44, s52
	s_add_u32 s46, s46, 0x80080
	s_addc_u32 s47, s47, 0
	s_add_u32 s80, s52, 0x100
	s_addc_u32 s81, s53, 0
	s_mov_b32 s84, -2
	v_add_u32_e32 v226, 0x10000, v237
	s_cmp_eq_u64 s[16:17], 0
	s_cbranch_scc1 .Lprio_g5
	s_setprio 1
